# XCD grid barrier: the first-arriving workgroup of each XCD starts the L2 write-back early so the last arriver's write-back on the critical path has less dirty data
# speedup vs baseline: 1.0023x; 1.0012x over previous
; __device__ __forceinline__ unsigned xb_ld(unsigned* p)              { return __hip_atomic_load(p, __ATOMIC_RELAXED, __HIP_MEMORY_SCOPE_AGENT); }
; __device__ __forceinline__ unsigned xb_add(unsigned* p, unsigned v) { return __hip_atomic_fetch_add(p, v, __ATOMIC_RELAXED, __HIP_MEMORY_SCOPE_AGENT); }
; #define XB_SPIN(cond, bar) do { unsigned _sp = 0; while (cond) { __builtin_amdgcn_s_sleep(1); \
;     if ((++_sp & 255u) == 0u) { if (xb_ld(&(bar)[XB_TMO])) break; if (_sp > XB_SPIN_CAP) { atomicAdd(&(bar)[XB_TMO], 1u); break; } } } } while (0)
; __device__ __forceinline__ void xcd_barrier(const XcdBarrier& b) {
;     ...
;         const unsigned old = xb_add(&bar[XB_XSUB(b.x)], 1u);
;         const unsigned gen = old / nloc;
;         if (old + 1u == (gen + 1u) * nloc) {
;             __builtin_amdgcn_fence(__ATOMIC_RELEASE, "agent");
;             asm volatile("s_waitcnt vmcnt(0)" ::: "memory");
;             const unsigned og = xb_add(&bar[XB_TOP], 1u);
;             const unsigned tg = og / nx;
;             if (og + 1u == (tg + 1u) * nx) xb_add(&bar[XB_TOPGEN], 1u);
;             else XB_SPIN(xb_ld(&bar[XB_TOPGEN]) == tg, bar);
;             __builtin_amdgcn_fence(__ATOMIC_ACQUIRE, "agent");
;             xb_add(&bar[XB_XGEN(b.x)], 1u);
;             asm volatile("s_waitcnt vmcnt(0)" ::: "memory");
;         } else {
;             XB_SPIN(xb_ld(&bar[XB_XGEN(b.x)]) == gen, bar);
.LBB0_974:
	s_or_b64 exec, exec, s[4:5]
	v_cvt_f32_u32_e32 v5, v3
	s_waitcnt vmcnt(0)
	v_readfirstlane_b32 s4, v4
	v_sub_u32_e32 v4, 0, v3
	v_rcp_iflag_f32_e32 v5, v5
	v_add_u32_e32 v6, s4, v0
	v_mul_f32_e32 v5, 0x4f7ffffe, v5
	v_cvt_u32_f32_e32 v5, v5
	v_mul_lo_u32 v0, v4, v5
	v_mul_hi_u32 v0, v5, v0
	v_add_u32_e32 v0, v5, v0
	v_mul_hi_u32 v0, v6, v0
	v_mul_lo_u32 v4, v0, v3
	v_sub_u32_e32 v4, v6, v4
	v_add_u32_e32 v5, 1, v0
	v_cmp_ge_u32_e32 vcc, v4, v3
	s_nop 1
	v_cndmask_b32_e32 v0, v0, v5, vcc
	v_sub_u32_e32 v5, v4, v3
	v_cndmask_b32_e32 v4, v4, v5, vcc
	v_add_u32_e32 v5, 1, v0
	v_cmp_ge_u32_e32 vcc, v4, v3
	v_add_u32_e32 v4, 1, v6
	s_nop 0
	v_cndmask_b32_e32 v0, v0, v5, vcc
	v_mul_lo_u32 v5, v3, v0
	v_add_u32_e32 v3, v5, v3
	v_cmp_ne_u32_e32 vcc, v4, v3
	s_and_saveexec_b64 s[4:5], vcc
	s_xor_b64 s[4:5], exec, s[4:5]
	s_cbranch_execz .LBB0_988
	v_cmp_eq_u32_e32 vcc, v6, v5
	s_cbranch_vccz .Lbar_nofirst
	buffer_wbl2 sc1
.Lbar_nofirst:
	v_readlane_b32 s6, v255, 15
	v_readlane_b32 s7, v255, 16
	s_waitcnt lgkmcnt(0)
	s_nop 3
	global_load_dword v2, v1, s[6:7] sc1
	s_waitcnt vmcnt(0)
	v_cmp_eq_u32_e32 vcc, v2, v0
	s_and_saveexec_b64 s[6:7], vcc
	s_cbranch_execz .LBB0_987
	s_mov_b32 s19, 1
	s_mov_b64 s[8:9], 0
	s_branch .LBB0_978
